# idle workgroups' weight prep / cache copies: write-through stores, the buffer_wbl2 release at the end removed (64 L2 write-backs per out-proj phase less)
# speedup vs baseline: 1.0271x; 1.0044x over previous
.LBB0_1162:
	s_or_b64 exec, exec, s[2:3]
	ds_read2_b32 v[12:13], v22 offset0:33 offset1:41
	ds_read2_b32 v[32:33], v22 offset1:8
	ds_read2_b32 v[34:35], v22 offset0:66 offset1:74
	ds_read2_b32 v[36:37], v22 offset0:99 offset1:107
	ds_read2_b32 v[38:39], v22 offset0:132 offset1:140
	ds_read2_b32 v[40:41], v22 offset0:165 offset1:173
	ds_read2_b32 v[42:43], v22 offset0:198 offset1:206
	ds_read2_b32 v[44:45], v22 offset0:231 offset1:239
	v_lshlrev_b32_e32 v112, 1, v28
	s_waitcnt lgkmcnt(6)
	v_mov_b32_e32 v28, v32
	v_mov_b32_e32 v29, v12
	s_waitcnt lgkmcnt(5)
	v_mov_b32_e32 v30, v34
	s_waitcnt lgkmcnt(4)
	v_mov_b32_e32 v31, v36
	v_lshlrev_b32_e32 v7, 5, v9
	v_lshl_add_u64 v[10:11], v[10:11], 0, v[112:113]
	v_mov_b32_e32 v9, v113
	s_waitcnt vmcnt(0)
	v_pk_mul_f32 v[28:29], v[14:15], v[28:29]
	v_pk_mul_f32 v[30:31], v[16:17], v[30:31]
	v_lshl_add_u64 v[10:11], v[10:11], 0, v[8:9]
	v_cvt_pk_bf16_f32 v28, v28, v29
	v_cvt_pk_bf16_f32 v29, v30, v31
	s_waitcnt lgkmcnt(3)
	v_mov_b32_e32 v30, v38
	s_waitcnt lgkmcnt(2)
	v_mov_b32_e32 v31, v40
	s_waitcnt lgkmcnt(1)
	v_mov_b32_e32 v46, v42
	s_waitcnt lgkmcnt(0)
	v_mov_b32_e32 v47, v44
	v_or_b32_e32 v9, v7, v5
	v_pk_mul_f32 v[30:31], v[18:19], v[30:31]
	v_pk_mul_f32 v[46:47], v[20:21], v[46:47]
	v_mul_lo_u32 v112, v27, v9
	v_mov_b32_e32 v12, v33
	v_cvt_pk_bf16_f32 v30, v30, v31
	v_cvt_pk_bf16_f32 v31, v46, v47
	v_lshl_add_u64 v[46:47], v[112:113], 1, v[10:11]
	v_pk_mul_f32 v[12:13], v[14:15], v[12:13]
	v_mov_b32_e32 v36, v35
	global_store_dwordx4 v[46:47], v[28:31], off sc1
	v_mov_b32_e32 v40, v39
	v_mov_b32_e32 v44, v43
	v_cvt_pk_bf16_f32 v28, v12, v13
	v_pk_mul_f32 v[12:13], v[16:17], v[36:37]
	v_or_b32_e32 v9, v7, v23
	v_cvt_pk_bf16_f32 v29, v12, v13
	v_pk_mul_f32 v[12:13], v[18:19], v[40:41]
	v_mul_lo_u32 v112, v27, v9
	v_cvt_pk_bf16_f32 v30, v12, v13
	v_pk_mul_f32 v[12:13], v[20:21], v[44:45]
	v_or_b32_e32 v9, v7, v24
	v_cvt_pk_bf16_f32 v31, v12, v13
	v_lshl_add_u64 v[12:13], v[112:113], 1, v[10:11]
	global_store_dwordx4 v[12:13], v[28:31], off sc1
	ds_read2_b32 v[12:13], v22 offset0:16 offset1:24
	ds_read2_b32 v[32:33], v22 offset0:49 offset1:57
	ds_read2_b32 v[34:35], v22 offset0:82 offset1:90
	ds_read2_b32 v[36:37], v22 offset0:115 offset1:123
	ds_read2_b32 v[38:39], v22 offset0:148 offset1:156
	ds_read2_b32 v[40:41], v22 offset0:181 offset1:189
	ds_read2_b32 v[42:43], v22 offset0:214 offset1:222
	ds_read2_b32 v[44:45], v22 offset0:247 offset1:255
	s_waitcnt lgkmcnt(7)
	v_mov_b32_e32 v28, v12
	s_waitcnt lgkmcnt(6)
	v_mov_b32_e32 v29, v32
	s_waitcnt lgkmcnt(5)
	v_mov_b32_e32 v30, v34
	s_waitcnt lgkmcnt(4)
	v_mov_b32_e32 v31, v36
	v_pk_mul_f32 v[28:29], v[14:15], v[28:29]
	v_pk_mul_f32 v[30:31], v[16:17], v[30:31]
	v_cvt_pk_bf16_f32 v28, v28, v29
	v_cvt_pk_bf16_f32 v29, v30, v31
	s_waitcnt lgkmcnt(3)
	v_mov_b32_e32 v30, v38
	s_waitcnt lgkmcnt(2)
	v_mov_b32_e32 v31, v40
	s_waitcnt lgkmcnt(1)
	v_mov_b32_e32 v46, v42
	s_waitcnt lgkmcnt(0)
	v_mov_b32_e32 v47, v44
	v_mov_b32_e32 v32, v13
	v_mov_b32_e32 v36, v35
	v_pk_mul_f32 v[30:31], v[18:19], v[30:31]
	v_pk_mul_f32 v[46:47], v[20:21], v[46:47]
	v_mul_lo_u32 v112, v27, v9
	v_pk_mul_f32 v[12:13], v[14:15], v[32:33]
	v_pk_mul_f32 v[14:15], v[16:17], v[36:37]
	v_mov_b32_e32 v40, v39
	v_mov_b32_e32 v44, v43
	v_or_b32_e32 v7, v7, v25
	v_cvt_pk_bf16_f32 v30, v30, v31
	v_cvt_pk_bf16_f32 v31, v46, v47
	v_lshl_add_u64 v[46:47], v[112:113], 1, v[10:11]
	v_cvt_pk_bf16_f32 v12, v12, v13
	v_cvt_pk_bf16_f32 v13, v14, v15
	v_pk_mul_f32 v[14:15], v[18:19], v[40:41]
	v_pk_mul_f32 v[16:17], v[20:21], v[44:45]
	v_mul_lo_u32 v112, v27, v7
	v_cvt_pk_bf16_f32 v14, v14, v15
	v_cvt_pk_bf16_f32 v15, v16, v17
	v_lshl_add_u64 v[10:11], v[112:113], 1, v[10:11]
	global_store_dwordx4 v[46:47], v[28:31], off sc1
	global_store_dwordx4 v[10:11], v[12:15], off sc1
	s_waitcnt lgkmcnt(0)
	v_add_u32_e32 v3, s33, v3
	v_cmp_le_i32_e32 vcc, s31, v3
	s_or_b64 s[6:7], vcc, s[6:7]
	s_andn2_b64 exec, exec, s[6:7]
	s_cbranch_execz .LBB0_1265

.LBB0_1268:
	s_or_b64 exec, exec, s[16:17]
	global_load_dwordx4 v[8:11], v[0:1], off
	global_load_dwordx4 v[12:15], v[0:1], off offset:16
	v_add_u32_e32 v7, s28, v7
	v_add_u32_e32 v0, 0x24000, v7
	s_mov_b32 s2, 0x63fff
	v_cmp_lt_i32_e32 vcc, s2, v0
	s_or_b64 s[12:13], vcc, s[12:13]
	v_add_u32_e32 v6, s29, v6
	s_waitcnt vmcnt(1)
	v_cvt_pk_bf16_f32 v8, v8, v9
	v_cvt_pk_bf16_f32 v9, v10, v11
	s_waitcnt vmcnt(0)
	v_cvt_pk_bf16_f32 v10, v12, v13
	v_cvt_pk_bf16_f32 v11, v14, v15
	global_store_dwordx4 v[2:3], v[8:11], off sc1
	s_andn2_b64 exec, exec, s[12:13]
	s_cbranch_execz .LBB0_1289

.LBB0_1291:
	v_ashrrev_i32_e32 v6, 11, v4
	v_cvt_f32_i32_e32 v6, v6
	v_bfe_u32 v7, v4, 5, 6
	v_cvt_f32_ubyte0_e32 v7, v7
	s_movk_i32 s2, 0x7fff
	v_cndmask_b32_e32 v6, v7, v6, vcc
	v_mul_f32_e32 v10, v6, v5
	v_mul_f32_e32 v11, 0.15915494, v10
	v_rndne_f32_e32 v11, v11
	v_fma_f32 v10, v10, 0.15915494, -v11
	v_and_b32_e32 v6, 0xffffffe0, v4
	v_cos_f32_e32 v11, v10
	v_ashrrev_i32_e32 v7, 31, v6
	v_lshlrev_b64 v[6:7], 2, v[6:7]
	v_lshl_add_u64 v[8:9], v[0:1], 0, v[6:7]
	global_store_dword v[8:9], v11, off sc1
	v_sin_f32_e32 v8, v10
	v_add_u32_e32 v4, s28, v4
	v_cmp_lt_i32_e64 s[4:5], s2, v4
	v_lshl_add_u64 v[6:7], v[2:3], 0, v[6:7]
	s_or_b64 s[8:9], s[4:5], s[8:9]
	global_store_dword v[6:7], v8, off sc1
	s_andn2_b64 exec, exec, s[8:9]
	s_cbranch_execnz .LBB0_1291

.LBB0_1293:
	s_waitcnt vmcnt(0)
	v_readlane_b32 s2, v254, 0
	v_readlane_b32 s3, v254, 1
	s_andn2_b64 vcc, exec, s[2:3]
	s_waitcnt lgkmcnt(0)
	s_barrier
	s_cbranch_vccnz .LBB0_1298
	v_mbcnt_lo_u32_b32 v0, -1, 0
	v_mbcnt_hi_u32_b32 v0, -1, v0
	s_nop 0
	v_cmp_eq_u32_e32 vcc, 0, v0
	s_and_saveexec_b64 s[4:5], vcc
	s_cbranch_execz .LBB0_1297
	s_mov_b64 s[6:7], exec
	v_mbcnt_lo_u32_b32 v0, s6, 0
	s_waitcnt vmcnt(0)
	s_waitcnt vmcnt(0)
	v_mbcnt_hi_u32_b32 v0, s7, v0
	v_cmp_eq_u32_e32 vcc, 0, v0
	s_mov_b64 s[2:3], s[0:1]
	s_and_b64 s[8:9], exec, vcc
	s_mov_b64 exec, s[8:9]
	s_cbranch_execz .LBB0_1297
	s_load_dwordx2 s[2:3], s[2:3], 0xd0
	s_lshl_b32 s8, s14, 6
	s_ashr_i32 s9, s8, 31
	s_lshl_b64 s[8:9], s[8:9], 2
	v_mov_b32_e32 v0, 0x50000
	s_waitcnt lgkmcnt(0)
	s_add_u32 s2, s2, s8
	s_addc_u32 s3, s3, s9
	s_bcnt1_i32_b64 s6, s[6:7]
	v_mov_b32_e32 v1, s6
	global_atomic_add v0, v1, s[2:3]
